# RWKV helper LDS-DMA addresses hoisted out of chunk loop; GDN output group: raw prefetch packed at end of stage 2, gate and gain loads issued at head of stage 4
# speedup vs baseline: 1.0219x; 1.0114x over previous
.LBB0_420:
	s_lshr_b32 s38, s61, 1
	s_cmp_eq_u32 s96, 0
	s_cselect_b64 s[40:41], -1, 0
	s_and_b64 s[36:37], s[40:41], exec
	s_cselect_b32 s59, 16, 32
	s_lshl_b32 s66, s96, 4
	v_mov_b32_e32 v171, 0
	s_cmp_ge_u32 s66, s59
	v_mov_b32_e32 v170, v171
	v_mov_b32_e32 v175, v171
	v_mov_b32_e32 v174, v171
	v_mov_b32_e32 v169, v171
	v_mov_b32_e32 v168, v171
	v_mov_b32_e32 v173, v171
	v_mov_b32_e32 v172, v171
	v_mov_b32_e32 v151, v171
	v_mov_b32_e32 v150, v171
	v_mov_b32_e32 v153, v171
	v_mov_b32_e32 v152, v171
	v_mov_b32_e32 v155, v171
	v_mov_b32_e32 v154, v171
	v_mov_b32_e32 v149, v171
	v_mov_b32_e32 v148, v171
	s_waitcnt lgkmcnt(0)
	s_barrier
	s_cbranch_scc1 .LBB0_573
	v_writelane_b32 v252, s40, 31
	v_cndmask_b32_e64 v54, 0, 1.0, s[6:7]
	s_waitcnt vmcnt(0)
	v_cndmask_b32_e64 v18, 0, 1.0, s[4:5]
	v_writelane_b32 v252, s41, 32
	v_cndmask_b32_e64 v19, 0, 1.0, s[34:35]
	v_readlane_b32 s6, v252, 27
	s_lshl_b32 s4, s6, 2
	s_add_u32 s34, s54, s4
	v_readlane_b32 s36, v252, 1
	s_addc_u32 s35, s55, 0
	s_lshl_b32 s92, s6, 1
	v_readlane_b32 s37, v252, 2
	v_cndmask_b32_e64 v17, 0, 1.0, s[2:3]
	s_add_u32 s2, s56, s92
	v_cndmask_b32_e64 v52, 0, 1.0, s[36:37]
	v_readlane_b32 s36, v252, 3
	s_addc_u32 s3, s57, 0
	v_readlane_b32 s37, v252, 4
	v_readlane_b32 s7, v252, 28
	v_writelane_b32 v252, s2, 33
	v_cndmask_b32_e64 v55, 0, 1.0, s[8:9]
	v_readlane_b32 s5, v253, 48
	v_writelane_b32 v252, s3, 34
	s_mul_i32 s2, s38, 0x41000
	s_add_i32 s2, s2, 0x3800000
	s_cmp_lt_u32 s61, 62
	s_cselect_b32 s8, s2, 0x2e81000
	s_cmp_lg_u32 s96, 0
	s_cselect_b64 s[40:41], -1, 0
	s_cmp_eq_u32 s96, 0
	v_writelane_b32 v252, s38, 35
	s_cselect_b64 s[2:3], -1, 0
	v_writelane_b32 v252, s2, 1
	v_cndmask_b32_e64 v56, 0, 1.0, s[10:11]
	v_cndmask_b32_e64 v57, 0, 1.0, s[12:13]
	v_writelane_b32 v252, s3, 2
	s_lshl_b64 s[2:3], s[52:53], 11
	s_add_u32 s10, s5, s2
	v_readlane_b32 s2, v253, 50
	s_addc_u32 s11, s2, s3
	v_writelane_b32 v252, s10, 36
	v_readlane_b32 s2, v253, 19
	v_cndmask_b32_e64 v58, 0, 1.0, s[14:15]
	v_writelane_b32 v252, s11, 37
	v_readlane_b32 s3, v253, 20
	v_readlane_b32 s12, v252, 15
	s_lshl_b64 s[2:3], s[2:3], 2
	v_readlane_b32 s14, v252, 17
	v_readlane_b32 s15, v252, 18
	s_add_u32 s2, s14, s2
	s_addc_u32 s3, s15, s3
	s_add_u32 s46, s2, s4
	s_addc_u32 s47, s3, 0
	s_mul_i32 s2, s97, 0x1800
	s_add_i32 s53, 0, 0x12000
	s_add_i32 s2, s53, s2
	v_readlane_b32 s13, v252, 16
	v_writelane_b32 v252, s2, 3
	s_lshl_b32 s2, s0, 2
	s_lshl_b32 s4, s0, 1
	s_add_i32 s9, s2, 0
	v_cndmask_b32_e64 v16, 0, 1.0, s[26:27]
	s_or_b32 s27, s6, s84
	s_add_i32 s55, s4, 0
	s_add_i32 s2, s9, 0x18500
	s_cmp_lg_u32 s97, 0
	s_cselect_b64 s[48:49], -1, 0
	s_cmp_eq_u32 s97, 3
	v_writelane_b32 v252, s2, 38
	s_cselect_b64 s[2:3], -1, 0
	s_add_i32 s5, s55, 0x20a00
	s_add_i32 s60, s60, -4
	s_cmp_eq_u32 s60, 0
	v_writelane_b32 v252, s5, 39
	s_cselect_b64 s[6:7], -1, 0
	v_writelane_b32 v252, s6, 40
	s_lshl_b32 s5, s60, 10
	s_add_i32 s4, s53, s4
	v_writelane_b32 v252, s7, 41
	v_writelane_b32 v252, s5, 42
	s_lshl_b32 s5, s97, 10
	s_add_i32 s5, s5, 0
	s_add_i32 s5, s5, 0x16800
	v_writelane_b32 v252, s5, 25
	s_lshl_b32 s5, s97, 9
	s_add_i32 s5, s5, 0
	s_add_i32 s5, s5, 0x17800
	s_cmp_gt_u32 s97, 1
	v_cndmask_b32_e64 v53, 0, 1.0, s[36:37]
	v_writelane_b32 v252, s5, 43
	s_cselect_b64 s[36:37], -1, 0
	s_cmp_eq_u32 s97, 1
	v_writelane_b32 v252, s4, 44
	s_cselect_b64 s[4:5], -1, 0
	s_cmp_eq_u32 s97, 2
	s_cselect_b64 s[6:7], -1, 0
	s_add_i32 s9, s9, 0x18400
	v_writelane_b32 v252, s9, 45
	s_lshl_b32 s9, s97, 12
	s_add_i32 s11, 0, 0x18600
	s_add_i32 s9, s11, s9
	v_writelane_b32 v252, s9, 5
	s_mul_i32 s9, s97, 0x900
	v_writelane_b32 v252, s9, 46
	s_or_b32 s9, s0, 1
	s_lshl_b32 s10, s9, 8
	s_add_i32 s10, s11, s10
	v_writelane_b32 v253, s10, 61
	s_mul_i32 s10, s9, 0x90
	v_writelane_b32 v252, s10, 47
	s_lshl_b32 s10, s0, 8
	s_add_i32 s61, s11, s10
	s_add_i32 s10, s61, 0x200
	v_writelane_b32 v253, s10, 63
	s_add_i32 s10, s61, 0x300
	v_writelane_b32 v252, s11, 48
	v_writelane_b32 v253, s10, 59
	s_add_i32 s10, s61, 0x400
	v_writelane_b32 v252, s10, 19
	s_add_i32 s10, s61, 0x500
	v_writelane_b32 v252, s10, 24
	s_add_i32 s10, s61, 0x600
	v_writelane_b32 v252, s10, 23
	s_mul_i32 s10, s97, 0x480
	s_nor_b64 s[44:45], s[40:41], s[28:29]
	s_add_i32 s43, s61, 0x700
	s_add_i32 s52, s61, 0x800
	s_add_i32 s54, s61, 0x900
	s_add_i32 s67, s61, 0xa00
	s_add_i32 s56, s61, 0xb00
	s_add_i32 s57, s61, 0xc00
	s_add_i32 s58, s61, 0xd00
	s_add_i32 s60, s61, 0xe00
	s_addk_i32 s61, 0xf00
	v_writelane_b32 v252, s10, 49
	s_mulk_i32 s9, 0x48
	v_writelane_b32 v252, s9, 50
	s_cmp_lg_u32 s97, 2
	s_mul_i32 s9, s96, 0x41000
	s_cselect_b64 s[82:83], -1, 0
	s_add_u32 s8, s9, s8
	s_addc_u32 s9, 0, 0
	s_add_u32 s8, s72, s8
	s_addc_u32 s9, s73, s9
	s_add_u32 s38, s8, 0xbdbf000
	s_addc_u32 s39, s9, 0
	s_lshl_b32 s8, s96, 10
	v_mov_b32_e32 v148, 0
	v_cndmask_b32_e64 v11, 0, 1.0, s[16:17]
	v_cndmask_b32_e64 v12, 0, 1.0, s[18:19]
	v_cndmask_b32_e64 v13, 0, 1.0, s[20:21]
	v_cndmask_b32_e64 v14, 0, 1.0, s[22:23]
	v_cndmask_b32_e64 v15, 0, 1.0, s[24:25]
	s_or_b32 s42, s8, 63
	v_mov_b32_e32 v149, v148
	v_mov_b32_e32 v154, v148
	v_mov_b32_e32 v155, v148
	v_mov_b32_e32 v152, v148
	v_mov_b32_e32 v153, v148
	v_mov_b32_e32 v150, v148
	v_mov_b32_e32 v151, v148
	v_mov_b32_e32 v172, v148
	v_mov_b32_e32 v173, v148
	v_mov_b32_e32 v168, v148
	v_mov_b32_e32 v169, v148
	v_mov_b32_e32 v174, v148
	v_mov_b32_e32 v175, v148
	v_mov_b32_e32 v170, v148
	v_mov_b32_e32 v171, v148
	s_mov_b32 s96, 0x2aaaaaab
	s_movk_i32 s97, 0xffe8
	v_writelane_b32 v252, s27, 51
	v_lshlrev_b32_e32 v192, 2, v161
	global_load_dword v196, v192, s[46:47] offset:1024
	global_load_dword v198, v192, s[46:47]
	global_load_dword v200, v192, s[46:47] offset:2048
	v_add_u32_e32 v192, s27, v161
	v_lshlrev_b32_e32 v192, 2, v192
	global_load_dword v197, v192, s[78:79]
	global_load_dword v201, v192, s[80:81]
	global_load_dword v192, v192, s[76:77]
	s_waitcnt vmcnt(0)
	v_add_u32_e32 v250, 0xffffff00, v190
	v_lshrrev_b32_e32 v224, 4, v250
	v_lshlrev_b32_e32 v224, 10, v224
	v_and_b32_e32 v251, 15, v250
	v_lshl_or_b32 v224, v251, 4, v224
	v_add_u32_e32 v225, 0x4000, v224
	v_add_u32_e32 v226, 0x8000, v224
	v_add_u32_e32 v227, 0xc000, v224
	v_min_u32_e32 v251, 15, v250
	v_lshlrev_b32_e32 v228, 4, v251
	v_add_u32_e32 v228, 0x10000, v228
	v_lshrrev_b32_e32 v229, 3, v250
	v_lshlrev_b32_e32 v229, 9, v229
	v_and_b32_e32 v251, 7, v250
	v_lshl_or_b32 v229, v251, 4, v229
	v_add_u32_e32 v242, 0x4000, v229
	s_mov_b32 s98, 0xaaaaaaab
	v_mov_b32_e32 v251, v250
	v_min_u32_e32 v251, 0x617, v251
	v_mul_hi_u32 v254, v251, s98
	v_lshrrev_b32_e32 v254, 4, v254
	v_mul_u32_u24_e32 v255, 24, v254
	v_sub_u32_e32 v255, v251, v255
	v_lshrrev_b32_e32 v255, 3, v255
	v_mul_u32_u24_e32 v243, 0x2200, v254
	v_lshl_add_u32 v243, v255, 9, v243
	v_and_b32_e32 v255, 7, v251
	v_lshl_add_u32 v243, v255, 4, v243
	v_add_u32_e32 v251, 0x100, v250
	v_min_u32_e32 v251, 0x617, v251
	v_mul_hi_u32 v254, v251, s98
	v_lshrrev_b32_e32 v254, 4, v254
	v_mul_u32_u24_e32 v255, 24, v254
	v_sub_u32_e32 v255, v251, v255
	v_lshrrev_b32_e32 v255, 3, v255
	v_mul_u32_u24_e32 v244, 0x2200, v254
	v_lshl_add_u32 v244, v255, 9, v244
	v_and_b32_e32 v255, 7, v251
	v_lshl_add_u32 v244, v255, 4, v244
	v_add_u32_e32 v251, 0x200, v250
	v_min_u32_e32 v251, 0x617, v251
	v_mul_hi_u32 v254, v251, s98
	v_lshrrev_b32_e32 v254, 4, v254
	v_mul_u32_u24_e32 v255, 24, v254
	v_sub_u32_e32 v255, v251, v255
	v_lshrrev_b32_e32 v255, 3, v255
	v_mul_u32_u24_e32 v245, 0x2200, v254
	v_lshl_add_u32 v245, v255, 9, v245
	v_and_b32_e32 v255, 7, v251
	v_lshl_add_u32 v245, v255, 4, v245
	v_add_u32_e32 v251, 0x300, v250
	v_min_u32_e32 v251, 0x617, v251
	v_mul_hi_u32 v254, v251, s98
	v_lshrrev_b32_e32 v254, 4, v254
	v_mul_u32_u24_e32 v255, 24, v254
	v_sub_u32_e32 v255, v251, v255
	v_lshrrev_b32_e32 v255, 3, v255
	v_mul_u32_u24_e32 v246, 0x2200, v254
	v_lshl_add_u32 v246, v255, 9, v246
	v_and_b32_e32 v255, 7, v251
	v_lshl_add_u32 v246, v255, 4, v246
	v_add_u32_e32 v251, 0x400, v250
	v_min_u32_e32 v251, 0x617, v251
	v_mul_hi_u32 v254, v251, s98
	v_lshrrev_b32_e32 v254, 4, v254
	v_mul_u32_u24_e32 v255, 24, v254
	v_sub_u32_e32 v255, v251, v255
	v_lshrrev_b32_e32 v255, 3, v255
	v_mul_u32_u24_e32 v247, 0x2200, v254
	v_lshl_add_u32 v247, v255, 9, v247
	v_and_b32_e32 v255, 7, v251
	v_lshl_add_u32 v247, v255, 4, v247
	v_add_u32_e32 v251, 0x500, v250
	v_min_u32_e32 v251, 0x617, v251
	v_mul_hi_u32 v254, v251, s98
	v_lshrrev_b32_e32 v254, 4, v254
	v_mul_u32_u24_e32 v255, 24, v254
	v_sub_u32_e32 v255, v251, v255
	v_lshrrev_b32_e32 v255, 3, v255
	v_mul_u32_u24_e32 v248, 0x2200, v254
	v_lshl_add_u32 v248, v255, 9, v248
	v_and_b32_e32 v255, 7, v251
	v_lshl_add_u32 v248, v255, 4, v248
	v_add_u32_e32 v251, 0x600, v250
	v_min_u32_e32 v251, 0x617, v251
	v_mul_hi_u32 v254, v251, s98
	v_lshrrev_b32_e32 v254, 4, v254
	v_mul_u32_u24_e32 v255, 24, v254
	v_sub_u32_e32 v255, v251, v255
	v_lshrrev_b32_e32 v255, 3, v255
	v_mul_u32_u24_e32 v249, 0x2200, v254
	v_lshl_add_u32 v249, v255, 9, v249
	v_and_b32_e32 v255, 7, v251
	v_lshl_add_u32 v249, v255, 4, v249

.LBB0_434:
	v_cndmask_b32_e64 v0, 0, 1, s[30:31]
	v_cmp_ne_u32_e64 s[10:11], 1, v0
	s_andn2_b64 vcc, exec, s[30:31]
	s_waitcnt lgkmcnt(0)
	s_barrier
	s_cbranch_vccnz .LBB0_455
	s_add_i32 s12, s66, 1
	s_cmp_ge_u32 s12, s59
	s_cbranch_scc1 .LBB0_439
	v_readlane_b32 s100, v252, 33
	v_readlane_b32 s101, v252, 34
	v_readlane_b32 s12, v252, 42
	v_readlane_b32 s14, v252, 40
	v_readlane_b32 s15, v252, 41
	s_nop 3
	s_lshl_b32 s98, s42, 10
	s_add_u32 s98, s34, s98
	s_addc_u32 s99, s35, 0
	s_add_i32 vcc_lo, s42, 1
	s_lshl_b32 vcc_lo, vcc_lo, 9
	s_add_u32 s100, s100, vcc_lo
	s_addc_u32 s101, s101, 0
	s_add_i32 m0, s12, 0x18600
	s_nop 0
	global_load_lds_dwordx4 v224, s[98:99]
	s_add_i32 m0, s12, 0x19600
	s_nop 0
	global_load_lds_dwordx4 v225, s[98:99]
	s_add_i32 m0, s12, 0x1a600
	s_nop 0
	global_load_lds_dwordx4 v226, s[98:99]
	s_add_i32 m0, s12, 0x1b600
	s_nop 0
	global_load_lds_dwordx4 v227, s[98:99]
	s_andn2_b64 vcc, exec, s[14:15]
	s_cbranch_vccnz .Lrw_dma_a5
	s_add_i32 m0, s12, 0x1c600
	s_nop 0
	global_load_lds_dwordx4 v228, s[98:99]
.Lrw_dma_a5:
	s_add_i32 m0, s12, 0x1ca00
	s_nop 0
	global_load_lds_dwordx4 v229, s[100:101]
	s_add_i32 m0, s12, 0x1da00
	s_nop 0
	global_load_lds_dwordx4 v242, s[100:101]

.LBB0_536:
	s_and_b64 vcc, exec, s[10:11]
	s_mov_b64 s[10:11], -1
	s_cbranch_vccnz .LBB0_567
	s_add_i32 s10, s66, 1
	v_mov_b32_e32 v46, v161
	s_cmp_ge_u32 s10, s59
	s_cbranch_scc1 .LBB0_540
	v_readlane_b32 s100, v252, 29
	v_readlane_b32 s101, v252, 30
	v_readlane_b32 s10, v252, 42
	v_readlane_b32 s12, v252, 40
	v_readlane_b32 s13, v252, 41
	s_nop 3
	s_mul_i32 s98, s42, 0x2200
	s_add_u32 s100, s100, s98
	s_addc_u32 s101, s101, 0
	s_add_u32 s100, s100, s92
	s_addc_u32 s101, s101, s93
	s_add_u32 s100, s100, 0x1200
	s_addc_u32 s101, s101, 0
	s_add_i32 m0, s10, 0x12000
	s_nop 0
	global_load_lds_dwordx4 v243, s[100:101]
	s_add_i32 m0, s10, 0x13000
	s_nop 0
	global_load_lds_dwordx4 v244, s[100:101]
	s_add_i32 m0, s10, 0x14000
	s_nop 0
	global_load_lds_dwordx4 v245, s[100:101]
	s_add_i32 m0, s10, 0x15000
	s_nop 0
	global_load_lds_dwordx4 v246, s[100:101]
	s_add_i32 m0, s10, 0x16000
	s_nop 0
	global_load_lds_dwordx4 v247, s[100:101]
	s_add_i32 m0, s10, 0x17000
	s_nop 0
	global_load_lds_dwordx4 v248, s[100:101]
	s_andn2_b64 vcc, exec, s[12:13]
	s_cbranch_vccnz .LBB0_540
	s_add_i32 m0, s10, 0x18000
	s_nop 0
	global_load_lds_dwordx4 v249, s[100:101]

.LBB0_633:
	s_add_i32 s57, s57, 1
	s_cmp_ge_u32 s57, s56
	s_cselect_b64 s[60:61], -1, 0
	v_mov_b32_e32 v8, v168
	s_and_b64 vcc, exec, s[60:61]
	s_waitcnt lgkmcnt(0)
	s_barrier
	s_cbranch_vccnz .LBB0_639
	v_add_u32_e32 v0, s53, v8
	v_ashrrev_i32_e32 v1, 31, v0
	s_mov_b64 s[10:11], -1
	s_and_b64 vcc, exec, s[8:9]
	v_lshlrev_b64 v[0:1], 1, v[0:1]
	s_cbranch_vccnz .LBB0_636
	s_add_u32 s10, s72, s27
	s_addc_u32 s11, s73, s0
	v_lshl_add_u64 v[4:5], s[10:11], 0, v[0:1]
	v_add_co_u32_e32 v6, vcc, 0x361c000, v4
	s_add_u32 s10, s72, s80
	s_nop 0
	v_addc_co_u32_e32 v7, vcc, 0, v5, vcc
	global_load_ushort v170, v[6:7], off
	global_load_ushort v161, v[6:7], off offset:1024
	v_add_co_u32_e32 v6, vcc, 0x361e000, v4
	s_addc_u32 s11, s73, s24
	s_nop 0
	v_addc_co_u32_e32 v7, vcc, 0, v5, vcc
	v_add_co_u32_e32 v4, vcc, 0x3620000, v4
	global_load_ushort v171, v[6:7], off offset:512
	global_load_ushort v224, v[6:7], off offset:1536
	v_addc_co_u32_e32 v5, vcc, 0, v5, vcc
	global_load_ushort v172, v[4:5], off offset:1024
	global_load_ushort v225, v[4:5], off offset:2048
	v_lshl_add_u64 v[4:5], s[10:11], 0, v[0:1]
	v_add_co_u32_e32 v4, vcc, 0x3688000, v4
	s_add_u32 s10, s72, s25
	s_nop 0
	v_addc_co_u32_e32 v5, vcc, 0, v5, vcc
	s_addc_u32 s11, s73, s26
	global_load_ushort v186, v[4:5], off offset:1536
	global_load_ushort v226, v[4:5], off offset:2560
	v_lshl_add_u64 v[4:5], s[10:11], 0, v[0:1]
	s_mov_b32 s10, 0x3602000
	v_add_co_u32_e32 v6, vcc, s10, v4
	s_mov_b32 s10, 0x3604000
	s_nop 0
	v_addc_co_u32_e32 v7, vcc, 0, v5, vcc
	global_load_ushort v187, v[6:7], off offset:2048
	global_load_ushort v227, v[6:7], off offset:3072
	v_add_co_u32_e32 v6, vcc, s10, v4
	s_mov_b32 s10, 0x3606000
	s_nop 0
	v_addc_co_u32_e32 v7, vcc, 0, v5, vcc
	global_load_ushort v188, v[6:7], off offset:2560
	global_load_ushort v228, v[6:7], off offset:3584
	v_add_co_u32_e32 v6, vcc, s10, v4
	s_mov_b32 s10, 0x3607000
	s_nop 0
	v_addc_co_u32_e32 v7, vcc, 0, v5, vcc
	global_load_ushort v189, v[6:7], off offset:3072
	v_add_co_u32_e32 v6, vcc, s10, v4
	s_mov_b32 s10, 0x3608000
	s_nop 0
	v_addc_co_u32_e32 v7, vcc, 0, v5, vcc
	global_load_ushort v229, v[6:7], off
	v_add_co_u32_e32 v6, vcc, s10, v4
	s_mov_b32 s10, 0x3609000
	s_nop 0
	v_addc_co_u32_e32 v7, vcc, 0, v5, vcc
	global_load_ushort v190, v[6:7], off offset:3584
	v_add_co_u32_e32 v6, vcc, s10, v4
	s_mov_b32 s10, 0x360b000
	s_nop 0
	v_addc_co_u32_e32 v7, vcc, 0, v5, vcc
	global_load_ushort v242, v[6:7], off offset:512
	v_add_co_u32_e32 v6, vcc, s10, v4
	s_mov_b32 s10, 0x360d000
	s_nop 0
	v_addc_co_u32_e32 v7, vcc, 0, v5, vcc
	global_load_ushort v191, v[6:7], off
	global_load_ushort v243, v[6:7], off offset:1024
	v_add_co_u32_e32 v6, vcc, s10, v4
	s_mov_b32 s10, 0x360f000
	s_nop 0
	v_addc_co_u32_e32 v7, vcc, 0, v5, vcc
	global_load_ushort v192, v[6:7], off offset:512
	global_load_ushort v244, v[6:7], off offset:1536
	v_add_co_u32_e32 v6, vcc, s10, v4
	s_mov_b32 s10, 0x3611000
	s_nop 0
	v_addc_co_u32_e32 v7, vcc, 0, v5, vcc
	global_load_ushort v193, v[6:7], off offset:1024
	global_load_ushort v245, v[6:7], off offset:2048
	v_add_co_u32_e32 v6, vcc, s10, v4
	s_mov_b32 s10, 0x3613000
	s_nop 0
	v_addc_co_u32_e32 v7, vcc, 0, v5, vcc
	global_load_ushort v194, v[6:7], off offset:1536
	global_load_ushort v246, v[6:7], off offset:2560
	v_add_co_u32_e32 v6, vcc, s10, v4
	s_mov_b32 s10, 0x3615000
	s_nop 0
	v_addc_co_u32_e32 v7, vcc, 0, v5, vcc
	global_load_ushort v195, v[6:7], off offset:2048
	global_load_ushort v247, v[6:7], off offset:3072
	v_add_co_u32_e32 v6, vcc, s10, v4
	s_mov_b32 s10, 0x3618000
	s_nop 0
	v_addc_co_u32_e32 v7, vcc, 0, v5, vcc
	global_load_ushort v196, v[6:7], off offset:2560
	global_load_ushort v248, v[6:7], off offset:3584
	v_add_co_u32_e32 v6, vcc, 0x3617000, v4
	s_nop 1
	v_addc_co_u32_e32 v7, vcc, 0, v5, vcc
	global_load_ushort v197, v[6:7], off offset:3072
	v_add_co_u32_e32 v6, vcc, s10, v4
	s_mov_b32 s10, 0x361c000
	s_nop 0
	v_addc_co_u32_e32 v7, vcc, 0, v5, vcc
	global_load_ushort v249, v[6:7], off
	v_add_co_u32_e32 v6, vcc, 0x3619000, v4
	s_nop 1
	v_addc_co_u32_e32 v7, vcc, 0, v5, vcc
	global_load_ushort v198, v[6:7], off offset:3584
	v_add_co_u32_e32 v6, vcc, 0x361a000, v4
	s_nop 1
	v_addc_co_u32_e32 v7, vcc, 0, v5, vcc
	global_load_ushort v250, v[6:7], off offset:512
	v_add_co_u32_e32 v6, vcc, s10, v4
	s_mov_b32 s10, 0x361e000
	s_nop 0
	v_addc_co_u32_e32 v7, vcc, 0, v5, vcc
	global_load_ushort v199, v[6:7], off
	global_load_ushort v251, v[6:7], off offset:1024
	v_add_co_u32_e32 v6, vcc, s10, v4
	s_mov_b64 s[10:11], 0
	s_nop 0
	v_addc_co_u32_e32 v7, vcc, 0, v5, vcc
	v_add_co_u32_e32 v4, vcc, 0x3620000, v4
	global_load_ushort v200, v[6:7], off offset:512
	s_nop 0
	global_load_ushort v254, v[6:7], off offset:1536
	v_addc_co_u32_e32 v5, vcc, 0, v5, vcc
	global_load_ushort v201, v[4:5], off offset:1024
	s_nop 0
	global_load_ushort v255, v[4:5], off offset:2048

.LBB0_648:
	v_cvt_pk_bf16_f32 v8, v9, v77
	v_cvt_pk_bf16_f32 v9, v78, v79
	s_mov_b64 s[10:11], 0
	ds_write_b64 v0, v[8:9] offset:64608
	s_waitcnt vmcnt(0)
	v_perm_b32 v173, v224, v161, s71
	v_perm_b32 v182, v226, v225, s71
	v_perm_b32 v181, v228, v227, s71
	v_perm_b32 v180, v242, v229, s71
	v_perm_b32 v179, v244, v243, s71
	v_perm_b32 v178, v246, v245, s71
	v_perm_b32 v177, v249, v248, s71
	v_perm_b32 v176, v248, v247, s71
	v_perm_b32 v175, v251, v250, s71
	v_perm_b32 v174, v255, v254, s71

.LBB0_714:
	v_mov_b32_e32 v0, v168
	s_mov_b64 s[12:13], -1
	v_and_b32_e32 v54, 15, v0
	s_and_b64 vcc, exec, s[44:45]
	v_or_b32_e32 v55, s55, v54
	v_and_b32_e32 v52, -16, v0
	v_mul_u32_u24_e32 v53, 0x90, v54
	s_cbranch_vccz .LBB0_736
	s_cmp_lg_u64 s[8:9], 0
	s_cbranch_scc0 .Lgd_noz
	v_readlane_b32 s100, v253, 50
	v_readlane_b32 s101, v253, 51
	s_add_i32 s98, s55, s54
	v_lshrrev_b32_e32 v74, 4, v0
	v_lshlrev_b32_e32 v74, 4, v74
	s_nop 2
	global_load_dwordx4 v[248:251], v74, s[100:101]
	global_load_dwordx4 v[68:71], v74, s[100:101] offset:64
	global_load_dwordx4 v[224:227], v74, s[100:101] offset:128
	global_load_dwordx4 v[242:245], v74, s[100:101] offset:192
	v_add_u32_e32 v74, s98, v54
	v_mul_u32_u24_e32 v74, 0x2200, v74
	v_lshrrev_b32_e32 v72, 4, v0
	v_lshl_add_u32 v72, v72, 2, s53
	v_lshl_add_u32 v74, v72, 1, v74
	v_add_u32_e32 v74, 0x1a00, v74
	global_load_dwordx2 v[254:255], v74, s[40:41]
	global_load_dwordx2 v[72:73], v74, s[40:41] offset:32
	global_load_dwordx2 v[228:229], v74, s[40:41] offset:64
	global_load_dwordx2 v[246:247], v74, s[40:41] offset:96
.Lgd_noz:
	v_mad_u32_u24 v1, v54, s89, 0
	v_add_u32_e32 v1, v1, v52
	ds_read_b128 v[8:11], v1 offset:27648
	v_mul_u32_u24_e32 v2, 0x90, v55
	v_add3_u32 v2, 0, v2, v52
	ds_read_b128 v[16:19], v2 offset:64512
	ds_read_b128 v[48:51], v2 offset:64576
	v_cndmask_b32_e64 v2, 0, 1, s[34:35]
	v_cmp_ne_u32_e64 s[12:13], 1, v2
	s_andn2_b64 vcc, exec, s[34:35]
	s_waitcnt lgkmcnt(1)
	v_mfma_f32_16x16x32_bf16 v[28:31], v[8:11], v[16:19], v[88:91]
	s_cbranch_vccnz .LBB0_717
	ds_read_b128 v[8:11], v1 offset:27712
	s_waitcnt lgkmcnt(0)
	v_mfma_f32_16x16x32_bf16 v[28:31], v[8:11], v[48:51], v[28:31]

.LBB0_733:
	s_and_b64 vcc, exec, s[14:15]
	s_cbranch_vccz .LBB0_735
	v_mul_f32_e32 v0, v29, v29
	v_mul_f32_e32 v1, v31, v31
	v_fmac_f32_e32 v0, v28, v28
	v_fmac_f32_e32 v1, v30, v30
	v_add_f32_e32 v0, v0, v1
	v_mul_f32_e32 v1, v33, v33
	v_mul_f32_e32 v2, v35, v35
	v_fmac_f32_e32 v1, v32, v32
	v_fmac_f32_e32 v2, v34, v34
	v_add_f32_e32 v1, v1, v2
	v_add_f32_e32 v0, v0, v1
	v_mul_f32_e32 v1, v41, v41
	v_mul_f32_e32 v2, v43, v43
	v_fmac_f32_e32 v1, v40, v40
	v_fmac_f32_e32 v2, v42, v42
	v_add_f32_e32 v1, v1, v2
	v_add_f32_e32 v2, v0, v1
	v_pk_mul_f32 v[0:1], v[46:47], v[46:47]
	v_pk_mul_f32 v[8:9], v[44:45], v[44:45]
	s_add_i32 s12, s55, s54
	v_pk_mov_b32 v[12:13], v[8:9], v[0:1] op_sel:[1,0]
	v_mov_b32_e32 v9, v1
	v_pk_add_f32 v[0:1], v[12:13], v[8:9]
	v_lshlrev_b32_e32 v8, 2, v10
	v_add_f32_e32 v0, v0, v1
	v_add_f32_e32 v0, v2, v0
	v_and_b32_e32 v2, 64, v234
	v_xor_b32_e32 v1, 16, v234
	v_add_u32_e32 v2, 64, v2
	v_cmp_lt_i32_e32 vcc, v1, v2
	v_ashrrev_i32_e32 v9, 31, v8
	v_add_u32_e32 v12, s53, v8
	v_cndmask_b32_e32 v1, v234, v1, vcc
	v_lshlrev_b32_e32 v1, 2, v1
	ds_bpermute_b32 v1, v1, v0
	v_ashrrev_i32_e32 v13, 31, v12
	v_lshlrev_b64 v[12:13], 1, v[12:13]
	s_waitcnt lgkmcnt(0)
	v_add_f32_e32 v0, v0, v1
	v_xor_b32_e32 v1, 32, v234
	v_cmp_lt_i32_e32 vcc, v1, v2
	v_add_u32_e32 v2, s12, v54
	v_readlane_b32 s12, v253, 50
	v_cndmask_b32_e32 v1, v234, v1, vcc
	v_lshlrev_b32_e32 v1, 2, v1
	ds_bpermute_b32 v1, v1, v0
	v_readlane_b32 s13, v253, 51
	s_waitcnt lgkmcnt(0)
	v_add_f32_e32 v0, v0, v1
	v_fmamk_f32 v0, v0, 0x3c800000, v158
	v_cmp_gt_f32_e32 vcc, s75, v0
	v_mul_f32_e32 v1, 0x4b800000, v0
	v_lshl_add_u64 v[14:15], v[8:9], 2, s[12:13]
	v_cndmask_b32_e32 v0, v0, v1, vcc
	v_mov_b64_e32 v[8:9], s[40:41]
	v_rsq_f32_e32 v0, v0
	v_mad_u64_u32 v[16:17], s[12:13], v2, s64, v[8:9]
	v_readlane_b32 s12, v253, 48
	v_lshlrev_b64 v[8:9], 11, v[2:3]
	v_readlane_b32 s13, v253, 49
	v_lshl_add_u64 v[20:21], v[16:17], 0, v[12:13]
	v_mul_f32_e32 v1, 0x45800000, v0
	v_lshl_add_u64 v[18:19], s[12:13], 0, v[8:9]
	s_mov_b64 s[12:13], 0x1a00
	v_lshl_add_u64 v[16:17], v[20:21], 0, s[12:13]
	s_movk_i32 s12, 0x1000
	v_cndmask_b32_e32 v0, v0, v1, vcc
	v_lshl_add_u64 v[12:13], v[18:19], 0, v[12:13]
	s_waitcnt vmcnt(0)
	v_mov_b64_e32 v[8:9], v[248:249]
	v_mov_b64_e32 v[10:11], v[250:251]
	v_mov_b64_e32 v[20:21], v[254:255]
	v_lshlrev_b32_e32 v22, 16, v20
	v_mul_f32_e32 v1, 0xbfb8aa3b, v22
	v_exp_f32_e32 v1, v1
	v_and_b32_e32 v23, 0xffff0000, v20
	v_lshlrev_b32_e32 v20, 16, v21
	v_and_b32_e32 v21, 0xffff0000, v21
	v_add_f32_e32 v1, 1.0, v1
	v_rcp_f32_e32 v24, v1
	v_pk_mul_f32 v[26:27], v[28:29], v[0:1] op_sel_hi:[1,0]
	v_mul_f32_e32 v1, 0xbfb8aa3b, v23
	v_exp_f32_e32 v1, v1
	v_pk_mul_f32 v[8:9], v[8:9], v[26:27]
	v_mov_b32_e32 v26, v82
	v_add_f32_e32 v1, 1.0, v1
	v_rcp_f32_e32 v25, v1
	v_mul_f32_e32 v1, 0xbfb8aa3b, v20
	v_exp_f32_e32 v1, v1
	v_pk_mul_f32 v[22:23], v[24:25], v[22:23]
	s_nop 0
	v_pk_mul_f32 v[8:9], v[22:23], v[8:9]
	v_add_f32_e32 v1, 1.0, v1
	v_rcp_f32_e32 v22, v1
	v_pk_mul_f32 v[24:25], v[30:31], v[0:1] op_sel_hi:[1,0]
	v_mul_f32_e32 v1, 0xbfb8aa3b, v21
	v_exp_f32_e32 v1, v1
	v_pk_mul_f32 v[10:11], v[10:11], v[24:25]
	v_cvt_pk_bf16_f32 v8, v8, v9
	v_add_f32_e32 v1, 1.0, v1
	v_rcp_f32_e32 v23, v1
	s_nop 0
	v_pk_mul_f32 v[20:21], v[22:23], v[20:21]
	s_nop 0
	v_pk_mul_f32 v[10:11], v[20:21], v[10:11]
	s_nop 0
	v_cvt_pk_bf16_f32 v9, v10, v11
	global_store_dwordx2 v[12:13], v[8:9], off offset:512
	v_mov_b64_e32 v[8:9], v[68:69]
	v_mov_b64_e32 v[10:11], v[70:71]
	v_mov_b64_e32 v[18:19], v[72:73]
	v_lshlrev_b32_e32 v20, 16, v18
	v_mul_f32_e32 v1, 0xbfb8aa3b, v20
	v_exp_f32_e32 v1, v1
	v_and_b32_e32 v21, 0xffff0000, v18
	v_lshlrev_b32_e32 v18, 16, v19
	v_and_b32_e32 v19, 0xffff0000, v19
	v_add_f32_e32 v1, 1.0, v1
	v_rcp_f32_e32 v22, v1
	v_pk_mul_f32 v[24:25], v[32:33], v[0:1] op_sel_hi:[1,0]
	v_mul_f32_e32 v1, 0xbfb8aa3b, v21
	v_exp_f32_e32 v1, v1
	v_pk_mul_f32 v[8:9], v[8:9], v[24:25]
	v_add_f32_e32 v1, 1.0, v1
	v_rcp_f32_e32 v23, v1
	v_mul_f32_e32 v1, 0xbfb8aa3b, v18
	v_exp_f32_e32 v1, v1
	v_pk_mul_f32 v[20:21], v[22:23], v[20:21]
	s_nop 0
	v_pk_mul_f32 v[8:9], v[8:9], v[20:21]
	v_add_f32_e32 v1, 1.0, v1
	v_rcp_f32_e32 v20, v1
	v_pk_mul_f32 v[22:23], v[34:35], v[0:1] op_sel_hi:[1,0]
	v_mul_f32_e32 v1, 0xbfb8aa3b, v19
	v_exp_f32_e32 v1, v1
	v_pk_mul_f32 v[10:11], v[10:11], v[22:23]
	v_cvt_pk_bf16_f32 v8, v8, v9
	v_add_f32_e32 v1, 1.0, v1
	v_rcp_f32_e32 v21, v1
	s_nop 0
	v_pk_mul_f32 v[18:19], v[20:21], v[18:19]
	s_nop 0
	v_pk_mul_f32 v[10:11], v[10:11], v[18:19]
	s_nop 0
	v_cvt_pk_bf16_f32 v9, v10, v11
	global_store_dwordx2 v[12:13], v[8:9], off offset:544
	v_mov_b64_e32 v[8:9], v[224:225]
	v_mov_b64_e32 v[10:11], v[226:227]
	v_mov_b64_e32 v[18:19], v[228:229]
	v_lshlrev_b32_e32 v20, 16, v18
	v_mul_f32_e32 v1, 0xbfb8aa3b, v20
	v_exp_f32_e32 v1, v1
	v_and_b32_e32 v21, 0xffff0000, v18
	v_lshlrev_b32_e32 v18, 16, v19
	v_and_b32_e32 v19, 0xffff0000, v19
	v_add_f32_e32 v1, 1.0, v1
	v_rcp_f32_e32 v22, v1
	v_pk_mul_f32 v[24:25], v[40:41], v[0:1] op_sel_hi:[1,0]
	v_mul_f32_e32 v1, 0xbfb8aa3b, v21
	v_exp_f32_e32 v1, v1
	v_pk_mul_f32 v[8:9], v[8:9], v[24:25]
	v_mov_b32_e32 v25, v81
	v_mov_b32_e32 v24, v80
	v_add_f32_e32 v1, 1.0, v1
	v_rcp_f32_e32 v23, v1
	v_mul_f32_e32 v1, 0xbfb8aa3b, v18
	v_exp_f32_e32 v1, v1
	v_pk_mul_f32 v[20:21], v[22:23], v[20:21]
	s_nop 0
	v_pk_mul_f32 v[8:9], v[8:9], v[20:21]
	v_add_f32_e32 v1, 1.0, v1
	v_rcp_f32_e32 v20, v1
	v_pk_mul_f32 v[22:23], v[42:43], v[0:1] op_sel_hi:[1,0]
	v_mul_f32_e32 v1, 0xbfb8aa3b, v19
	v_exp_f32_e32 v1, v1
	v_pk_mul_f32 v[10:11], v[10:11], v[22:23]
	v_cvt_pk_bf16_f32 v8, v8, v9
	v_mov_b32_e32 v23, v7
	v_add_f32_e32 v1, 1.0, v1
	v_rcp_f32_e32 v21, v1
	v_mov_b32_e32 v22, v6
	v_pk_mul_f32 v[18:19], v[20:21], v[18:19]
	s_nop 0
	v_pk_mul_f32 v[10:11], v[10:11], v[18:19]
	s_nop 0
	v_cvt_pk_bf16_f32 v9, v10, v11
	global_store_dwordx2 v[12:13], v[8:9], off offset:576
	v_mov_b64_e32 v[8:9], v[242:243]
	v_mov_b64_e32 v[10:11], v[244:245]
	v_mov_b64_e32 v[14:15], v[246:247]
	v_lshlrev_b32_e32 v16, 16, v14
	v_mul_f32_e32 v1, 0xbfb8aa3b, v16
	v_exp_f32_e32 v1, v1
	v_and_b32_e32 v17, 0xffff0000, v14
	v_lshlrev_b32_e32 v14, 16, v15
	v_and_b32_e32 v15, 0xffff0000, v15
	v_add_f32_e32 v1, 1.0, v1
	v_rcp_f32_e32 v18, v1
	v_pk_mul_f32 v[20:21], v[44:45], v[0:1] op_sel_hi:[1,0]
	v_mul_f32_e32 v1, 0xbfb8aa3b, v17
	v_exp_f32_e32 v1, v1
	v_mul_f32_e32 v2, 0xbfb8aa3b, v15
	v_exp_f32_e32 v2, v2
	v_pk_mul_f32 v[8:9], v[20:21], v[8:9]
	v_add_f32_e32 v1, 1.0, v1
	v_rcp_f32_e32 v19, v1
	v_mul_f32_e32 v1, 0xbfb8aa3b, v14
	v_exp_f32_e32 v1, v1
	v_add_f32_e32 v2, 1.0, v2
	v_pk_mul_f32 v[16:17], v[18:19], v[16:17]
	v_mov_b32_e32 v19, v59
	v_add_f32_e32 v1, 1.0, v1
	v_pk_mul_f32 v[8:9], v[8:9], v[16:17]
	v_rcp_f32_e32 v16, v1
	v_rcp_f32_e32 v17, v2
	v_pk_mul_f32 v[0:1], v[46:47], v[0:1] op_sel_hi:[1,0]
	v_cvt_pk_bf16_f32 v8, v8, v9
	v_pk_mul_f32 v[0:1], v[0:1], v[10:11]
	v_pk_mul_f32 v[10:11], v[16:17], v[14:15]
	v_mov_b32_e32 v18, v58
	v_pk_mul_f32 v[0:1], v[0:1], v[10:11]
	v_mov_b32_e32 v17, v57
	v_cvt_pk_bf16_f32 v9, v0, v1
	global_store_dwordx2 v[12:13], v[8:9], off offset:608
	v_mov_b32_e32 v16, v56
	v_mov_b32_e32 v15, v39
	v_mov_b32_e32 v14, v38
	v_mov_b32_e32 v13, v37
	v_mov_b32_e32 v12, v36
	v_mov_b32_e32 v11, v83
	v_mov_b32_e32 v21, v5
	v_mov_b32_e32 v20, v4

	.amdhsa_kernel _Z6mk_fwd4Args
		.amdhsa_group_segment_fixed_size 0
		.amdhsa_private_segment_fixed_size 0
		.amdhsa_kernarg_size 488
		.amdhsa_user_sgpr_count 2
		.amdhsa_user_sgpr_dispatch_ptr 0
		.amdhsa_user_sgpr_queue_ptr 0
		.amdhsa_user_sgpr_kernarg_segment_ptr 1
		.amdhsa_user_sgpr_dispatch_id 0
		.amdhsa_user_sgpr_kernarg_preload_length 0
		.amdhsa_user_sgpr_kernarg_preload_offset 0
		.amdhsa_user_sgpr_private_segment_size 0
		.amdhsa_uses_dynamic_stack 0
		.amdhsa_enable_private_segment 0
		.amdhsa_system_sgpr_workgroup_id_x 1
		.amdhsa_system_sgpr_workgroup_id_y 0
		.amdhsa_system_sgpr_workgroup_id_z 0
		.amdhsa_system_sgpr_workgroup_info 0
		.amdhsa_system_vgpr_workitem_id 0
		.amdhsa_next_free_vgpr 256
		.amdhsa_next_free_sgpr 102
		.amdhsa_accum_offset 256
		.amdhsa_reserve_vcc 1
		.amdhsa_float_round_mode_32 0
		.amdhsa_float_round_mode_16_64 0
		.amdhsa_float_denorm_mode_32 3
		.amdhsa_float_denorm_mode_16_64 3
		.amdhsa_dx10_clamp 1
		.amdhsa_ieee_mode 1
		.amdhsa_fp16_overflow 0
		.amdhsa_tg_split 0
		.amdhsa_exception_fp_ieee_invalid_op 0
		.amdhsa_exception_fp_denorm_src 0
		.amdhsa_exception_fp_ieee_div_zero 0
		.amdhsa_exception_fp_ieee_overflow 0
		.amdhsa_exception_fp_ieee_underflow 0
		.amdhsa_exception_fp_ieee_inexact 0
		.amdhsa_exception_int_div_zero 0
	.end_amdhsa_kernel

.Lfunc_end0:
	.size	_Z6mk_fwd4Args, .Lfunc_end0-_Z6mk_fwd4Args
	.set _Z6mk_fwd4Args.num_vgpr, 256
	.set _Z6mk_fwd4Args.num_agpr, 0
	.set _Z6mk_fwd4Args.numbered_sgpr, 102
	.set _Z6mk_fwd4Args.num_named_barrier, 0
	.set _Z6mk_fwd4Args.private_seg_size, 0
	.set _Z6mk_fwd4Args.uses_vcc, 1
	.set _Z6mk_fwd4Args.uses_flat_scratch, 0
	.set _Z6mk_fwd4Args.has_dyn_sized_stack, 0
	.set _Z6mk_fwd4Args.has_recursion, 0
	.set _Z6mk_fwd4Args.has_indirect_call, 0

amdhsa.kernels:
  - .agpr_count:     0
    .args:
      - .offset:         0
        .size:           232
        .value_kind:     by_value
      - .offset:         232
        .size:           4
        .value_kind:     hidden_block_count_x
      - .offset:         236
        .size:           4
        .value_kind:     hidden_block_count_y
      - .offset:         240
        .size:           4
        .value_kind:     hidden_block_count_z
      - .offset:         244
        .size:           2
        .value_kind:     hidden_group_size_x
      - .offset:         246
        .size:           2
        .value_kind:     hidden_group_size_y
      - .offset:         248
        .size:           2
        .value_kind:     hidden_group_size_z
      - .offset:         250
        .size:           2
        .value_kind:     hidden_remainder_x
      - .offset:         252
        .size:           2
        .value_kind:     hidden_remainder_y
      - .offset:         254
        .size:           2
        .value_kind:     hidden_remainder_z
      - .offset:         272
        .size:           8
        .value_kind:     hidden_global_offset_x
      - .offset:         280
        .size:           8
        .value_kind:     hidden_global_offset_y
      - .offset:         288
        .size:           8
        .value_kind:     hidden_global_offset_z
      - .offset:         296
        .size:           2
        .value_kind:     hidden_grid_dims
      - .offset:         352
        .size:           4
        .value_kind:     hidden_dynamic_lds_size
    .group_segment_fixed_size: 0
    .kernarg_segment_align: 8
    .kernarg_segment_size: 488
    .language:       OpenCL C
    .language_version:
      - 2
      - 0
    .max_flat_workgroup_size: 512
    .name:           _Z6mk_fwd4Args
    .private_segment_fixed_size: 0
    .sgpr_count:     108
    .sgpr_spill_count: 166
    .symbol:         _Z6mk_fwd4Args.kd
    .uniform_work_group_size: 1
    .uses_dynamic_stack: false
    .vgpr_count:     256
    .vgpr_spill_count: 0
    .wavefront_size: 64
